# v49 + 8th FFN-up store pair merged + attention O-store lane exchange by DPP quad_perm instead of ds_bpermute (256 LDS round trips removed)
# speedup vs baseline: 1.0075x; 1.0017x over previous
.LBB0_1411:
	s_or_b64 exec, exec, s[18:19]
	v_cvt_f32_i32_e32 v57, v57
	v_cvt_f32_i32_e32 v56, v56
	v_cvt_f32_i32_e32 v55, v55
	v_cvt_f32_i32_e32 v54, v54
	v_cvt_f32_i32_e32 v53, v53
	v_cvt_f32_i32_e32 v52, v52
	v_cvt_f32_i32_e32 v51, v51
	v_cvt_f32_i32_e32 v50, v50
	v_pk_mul_f32 v[56:57], v[130:131], v[56:57] op_sel_hi:[0,1]
	v_pk_fma_f32 v[190:191], v[56:57], v[200:201], v[202:203]
	v_pk_mul_f32 v[54:55], v[130:131], v[54:55] op_sel_hi:[0,1]
	v_pk_mul_f32 v[52:53], v[130:131], v[52:53] op_sel:[1,0]
	v_pk_fma_f32 v[190:191], v[114:115], v[68:69], v[190:191]
	v_pk_fma_f32 v[192:193], v[54:55], v[116:117], v[204:205]
	v_pk_fma_f32 v[72:73], v[110:111], v[72:73], v[190:191]
	v_pk_fma_f32 v[190:191], v[52:53], v[200:201], v[202:203]
	v_cvt_f32_i32_e32 v41, v41
	v_cvt_f32_i32_e32 v40, v40
	v_pk_mul_f32 v[50:51], v[130:131], v[50:51] op_sel:[1,0]
	v_pk_fma_f32 v[192:193], v[112:113], v[66:67], v[192:193]
	v_pk_fma_f32 v[190:191], v[56:57], v[114:115], v[190:191]
	v_pk_fma_f32 v[134:135], v[134:135], v[200:201], v[202:203]
	v_cvt_f32_i32_e32 v49, v49
	v_cvt_f32_i32_e32 v48, v48
	v_cvt_f32_i32_e32 v47, v47
	v_cvt_f32_i32_e32 v46, v46
	v_cvt_f32_i32_e32 v35, v35
	v_cvt_f32_i32_e32 v37, v37
	v_cvt_f32_i32_e32 v36, v36
	v_cvt_f32_i32_e32 v34, v34
	v_pk_fma_f32 v[70:71], v[108:109], v[70:71], v[192:193]
	v_pk_fma_f32 v[192:193], v[50:51], v[116:117], v[204:205]
	v_pk_fma_f32 v[68:69], v[110:111], v[68:69], v[190:191]
	v_pk_fma_f32 v[190:191], v[86:87], v[200:201], v[202:203]
	v_pk_fma_f32 v[86:87], v[86:87], v[114:115], v[134:135]
	v_cvt_f32_i32_e32 v39, v39
	v_cvt_f32_i32_e32 v38, v38
	v_pk_fma_f32 v[192:193], v[54:55], v[112:113], v[192:193]
	v_pk_fma_f32 v[190:191], v[52:53], v[114:115], v[190:191]
	v_pk_fma_f32 v[52:53], v[52:53], v[110:111], v[86:87]
	v_cvt_f32_i32_e32 v45, v45
	v_cvt_f32_i32_e32 v44, v44
	v_cvt_f32_i32_e32 v43, v43
	v_cvt_f32_i32_e32 v42, v42
	v_mov_b32_e32 v86, v132
	v_mov_b32_e32 v87, v132
	v_mov_b32_e32 v90, v133
	v_mov_b32_e32 v91, v133
	v_pk_fma_f32 v[66:67], v[108:109], v[66:67], v[192:193]
	v_pk_fma_f32 v[192:193], v[88:89], v[116:117], v[204:205]
	v_pk_fma_f32 v[116:117], v[136:137], v[116:117], v[204:205]
	v_pk_mul_f32 v[40:41], v[86:87], v[40:41]
	v_mov_b32_e32 v86, v133
	v_mov_b32_e32 v87, v133
	v_mov_b32_e32 v92, v132
	v_mov_b32_e32 v93, v132
	v_pk_fma_f32 v[88:89], v[88:89], v[112:113], v[116:117]
	v_pk_mul_f32 v[36:37], v[86:87], v[36:37]
	v_pk_mul_f32 v[34:35], v[90:91], v[34:35]
	v_pk_mul_f32 v[46:47], v[130:131], v[46:47] op_sel_hi:[0,1]
	v_pk_mul_f32 v[48:49], v[130:131], v[48:49] op_sel_hi:[0,1]
	v_pk_fma_f32 v[192:193], v[50:51], v[112:113], v[192:193]
	v_pk_fma_f32 v[50:51], v[50:51], v[108:109], v[88:89]
	v_pk_mul_f32 v[38:39], v[92:93], v[38:39]
	s_waitcnt lgkmcnt(0)
	v_mov_b32_dpp v58, v34 row_shr:1 row_mask:0xf bank_mask:0xf
	v_mov_b32_dpp v59, v35 row_shr:1 row_mask:0xf bank_mask:0xf
	v_mov_b32_dpp v60, v36 row_shr:1 row_mask:0xf bank_mask:0xf
	v_mov_b32_dpp v61, v37 row_shr:1 row_mask:0xf bank_mask:0xf
	v_pk_fma_f32 v[86:87], v[48:49], v[98:99], v[102:103]
	v_pk_fma_f32 v[88:89], v[46:47], v[84:85], v[106:107]
	v_mov_b32_dpp v62, v38 row_shr:1 row_mask:0xf bank_mask:0xf
	v_mov_b32_dpp v63, v39 row_shr:1 row_mask:0xf bank_mask:0xf
	v_mov_b32_dpp v64, v40 row_shr:1 row_mask:0xf bank_mask:0xf
	v_mov_b32_dpp v65, v41 row_shr:1 row_mask:0xf bank_mask:0xf
	v_pk_mul_f32 v[42:43], v[130:131], v[42:43] op_sel:[1,0]
	v_pk_mul_f32 v[44:45], v[130:131], v[44:45] op_sel:[1,0]
	v_pk_fma_f32 v[86:87], v[82:83], v[60:61], v[86:87]
	v_pk_fma_f32 v[88:89], v[80:81], v[58:59], v[88:89]
	v_pk_fma_f32 v[64:65], v[78:79], v[64:65], v[86:87]
	v_pk_fma_f32 v[62:63], v[76:77], v[62:63], v[88:89]
	v_pk_fma_f32 v[86:87], v[44:45], v[98:99], v[102:103]
	v_pk_fma_f32 v[88:89], v[42:43], v[84:85], v[106:107]
	v_pk_fma_f32 v[86:87], v[48:49], v[82:83], v[86:87]
	v_pk_fma_f32 v[88:89], v[46:47], v[80:81], v[88:89]
	v_pk_fma_f32 v[36:37], v[36:37], v[98:99], v[102:103]
	v_pk_fma_f32 v[34:35], v[34:35], v[84:85], v[106:107]
	v_pk_fma_f32 v[60:61], v[78:79], v[60:61], v[86:87]
	v_pk_fma_f32 v[58:59], v[76:77], v[58:59], v[88:89]
	v_pk_fma_f32 v[86:87], v[40:41], v[98:99], v[102:103]
	v_pk_fma_f32 v[88:89], v[38:39], v[84:85], v[106:107]
	v_pk_fma_f32 v[36:37], v[40:41], v[82:83], v[36:37]
	v_pk_fma_f32 v[34:35], v[38:39], v[80:81], v[34:35]
	v_exp_f32_e64 v38, -v70
	v_exp_f32_e64 v40, -v72
	v_exp_f32_e64 v41, -v73
	v_exp_f32_e64 v39, -v71
	v_pk_fma_f32 v[88:89], v[42:43], v[80:81], v[88:89]
	v_pk_fma_f32 v[86:87], v[44:45], v[82:83], v[86:87]
	v_pk_add_f32 v[40:41], v[40:41], 1.0 op_sel_hi:[1,0]
	v_pk_add_f32 v[38:39], v[38:39], 1.0 op_sel_hi:[1,0]
	v_rcp_f32_e32 v40, v40
	v_rcp_f32_e32 v38, v38
	v_rcp_f32_e32 v41, v41
	v_rcp_f32_e32 v39, v39
	v_pk_fma_f32 v[36:37], v[44:45], v[78:79], v[36:37]
	v_pk_fma_f32 v[34:35], v[42:43], v[76:77], v[34:35]
	v_pk_mul_f32 v[42:43], v[72:73], v[64:65]
	v_pk_mul_f32 v[44:45], v[70:71], v[62:63]
	v_pk_mul_f32 v[40:41], v[40:41], v[42:43]
	v_pk_mul_f32 v[38:39], v[38:39], v[44:45]
	v_exp_f32_e64 v44, -v66
	v_exp_f32_e64 v62, -v68
	v_exp_f32_e64 v63, -v69
	v_exp_f32_e64 v45, -v67
	v_pk_fma_f32 v[46:47], v[46:47], v[76:77], v[88:89]
	v_add_u32_e32 v76, 0x80, v188
	v_cvt_pk_bf16_f32 v242, v38, v39
	v_cvt_pk_bf16_f32 v243, v40, v41
	v_mov_b64_e32 v[40:41], s[58:59]
	v_mad_i64_i32 v[42:43], s[18:19], v76, s17, v[40:41]
	v_lshl_add_u64 v[98:99], v[42:43], 0, v[74:75]
	v_pk_add_f32 v[38:39], v[62:63], 1.0 op_sel_hi:[1,0]
	v_pk_add_f32 v[42:43], v[44:45], 1.0 op_sel_hi:[1,0]
	v_rcp_f32_e32 v38, v38
	v_rcp_f32_e32 v42, v42
	v_rcp_f32_e32 v39, v39
	v_rcp_f32_e32 v43, v43
	v_pk_fma_f32 v[56:57], v[56:57], v[110:111], v[190:191]
	v_pk_fma_f32 v[54:55], v[54:55], v[108:109], v[192:193]
	v_pk_mul_f32 v[44:45], v[68:69], v[60:61]
	v_pk_mul_f32 v[58:59], v[66:67], v[58:59]
	v_pk_mul_f32 v[38:39], v[38:39], v[44:45]
	v_pk_mul_f32 v[42:43], v[42:43], v[58:59]
	v_exp_f32_e64 v44, -v54
	v_exp_f32_e64 v58, -v56
	v_exp_f32_e64 v59, -v57
	v_exp_f32_e64 v45, -v55
	v_cvt_pk_bf16_f32 v246, v42, v43
	v_cvt_pk_bf16_f32 v247, v38, v39
	v_add_u32_e32 v38, 0x81, v188
	v_mad_i64_i32 v[38:39], s[18:19], v38, s17, v[40:41]
	v_lshl_add_u64 v[102:103], v[38:39], 0, v[74:75]
	v_pk_add_f32 v[38:39], v[58:59], 1.0 op_sel_hi:[1,0]
	v_pk_add_f32 v[42:43], v[44:45], 1.0 op_sel_hi:[1,0]
	v_rcp_f32_e32 v38, v38
	v_rcp_f32_e32 v42, v42
	v_rcp_f32_e32 v39, v39
	v_rcp_f32_e32 v43, v43
	v_pk_fma_f32 v[48:49], v[48:49], v[78:79], v[86:87]
	v_pk_mul_f32 v[44:45], v[54:55], v[46:47]
	v_pk_mul_f32 v[46:47], v[56:57], v[48:49]
	v_pk_mul_f32 v[42:43], v[44:45], v[42:43]
	v_pk_mul_f32 v[38:39], v[46:47], v[38:39]
	v_exp_f32_e64 v44, -v50
	v_exp_f32_e64 v46, -v52
	v_exp_f32_e64 v47, -v53
	v_exp_f32_e64 v45, -v51
	v_cvt_pk_bf16_f32 v250, v42, v43
	v_cvt_pk_bf16_f32 v251, v38, v39
	v_add_u32_e32 v38, 0x82, v188
	v_mad_i64_i32 v[38:39], s[18:19], v38, s17, v[40:41]
	v_lshl_add_u64 v[106:107], v[38:39], 0, v[74:75]
	v_pk_add_f32 v[38:39], v[46:47], 1.0 op_sel_hi:[1,0]
	v_pk_add_f32 v[42:43], v[44:45], 1.0 op_sel_hi:[1,0]
	v_rcp_f32_e32 v38, v38
	v_rcp_f32_e32 v42, v42
	v_rcp_f32_e32 v39, v39
	v_rcp_f32_e32 v43, v43
	v_pk_mul_f32 v[36:37], v[52:53], v[36:37]
	v_pk_mul_f32 v[34:35], v[50:51], v[34:35]
	v_pk_mul_f32 v[36:37], v[36:37], v[38:39]
	v_pk_mul_f32 v[34:35], v[34:35], v[42:43]
	v_mov_b32_e32 v66, 0
	v_cvt_pk_bf16_f32 v206, v34, v35
	v_cvt_pk_bf16_f32 v207, v36, v37
	v_add_u32_e32 v36, 0x83, v188
	v_mad_i64_i32 v[36:37], s[18:19], v36, s17, v[40:41]
	v_lshl_add_u64 v[108:109], v[36:37], 0, v[74:75]
	ds_read_b128 v[74:77], v241 offset:16
	ds_read_b128 v[50:53], v241 offset:528
	ds_read_b128 v[82:85], v241 offset:1040
	ds_read_b128 v[46:49], v241 offset:1552
	ds_read_b128 v[78:81], v241 offset:2064
	ds_read_b128 v[42:45], v241 offset:2576
	ds_read_b128 v[70:73], v241 offset:3088
	ds_read_b128 v[38:41], v241 offset:3600
	ds_read_b128 v[86:89], v241 offset:4112
	ds_read_b128 v[54:57], v241 offset:4624
	v_mov_b32_e32 v34, 0
	v_mov_b32_e32 v67, 0
	v_mov_b32_e32 v68, 0
	v_mov_b32_e32 v69, 0
	v_mov_b32_e32 v62, 0
	v_mov_b32_e32 v63, 0
	v_mov_b32_e32 v64, 0
	v_mov_b32_e32 v65, 0
	s_and_saveexec_b64 s[18:19], s[6:7]
	s_cbranch_execz .LBB0_1413
	ds_read_b128 v[66:69], v240 offset:128
	ds_read_b128 v[62:65], v240 offset:144

.LBB0_1419:
	s_or_b64 exec, exec, s[6:7]
	v_cvt_f32_i32_e32 v23, v23
	v_cvt_f32_i32_e32 v22, v22
	v_cvt_f32_i32_e32 v25, v25
	v_cvt_f32_i32_e32 v24, v24
	v_cvt_f32_i32_e32 v21, v21
	v_cvt_f32_i32_e32 v20, v20
	v_mov_b32_e32 v86, v131
	v_mov_b32_e32 v87, v131
	v_cvt_f32_i32_e32 v17, v17
	v_cvt_f32_i32_e32 v16, v16
	v_cvt_f32_i32_e32 v5, v5
	v_cvt_f32_i32_e32 v4, v4
	v_mov_b32_e32 v88, v131
	v_mov_b32_e32 v89, v131
	v_pk_mul_f32 v[94:95], v[86:87], v[22:23]
	v_pk_fma_f32 v[22:23], v[60:61], v[84:85], v[72:73]
	v_cvt_f32_i32_e32 v15, v15
	v_cvt_f32_i32_e32 v14, v14
	v_cvt_f32_i32_e32 v9, v9
	v_cvt_f32_i32_e32 v8, v8
	v_cvt_f32_i32_e32 v3, v3
	v_cvt_f32_i32_e32 v2, v2
	v_pk_mul_f32 v[24:25], v[88:89], v[24:25]
	v_pk_fma_f32 v[60:61], v[66:67], v[82:83], v[70:71]
	v_pk_fma_f32 v[22:23], v[32:33], v[80:81], v[22:23]
	v_cvt_f32_i32_e32 v67, v19
	v_cvt_f32_i32_e32 v66, v18
	v_mov_b32_e32 v131, v130
	v_pk_fma_f32 v[32:33], v[32:33], v[84:85], v[72:73]
	v_cvt_f32_i32_e32 v13, v13
	v_cvt_f32_i32_e32 v12, v12
	v_cvt_f32_i32_e32 v7, v7
	v_cvt_f32_i32_e32 v6, v6
	v_pk_fma_f32 v[22:23], v[24:25], v[74:75], v[22:23]
	v_pk_mul_f32 v[20:21], v[130:131], v[20:21]
	v_pk_fma_f32 v[32:33], v[24:25], v[80:81], v[32:33]
	v_pk_fma_f32 v[24:25], v[24:25], v[84:85], v[72:73]
	v_cvt_f32_i32_e32 v11, v11
	v_cvt_f32_i32_e32 v10, v10
	v_mov_b32_e32 v68, v130
	v_mov_b32_e32 v69, v130
	v_pk_fma_f32 v[32:33], v[20:21], v[74:75], v[32:33]
	v_pk_fma_f32 v[24:25], v[20:21], v[80:81], v[24:25]
	v_pk_fma_f32 v[20:21], v[20:21], v[84:85], v[72:73]
	v_pk_mul_f32 v[4:5], v[132:133], v[4:5]
	v_pk_mul_f32 v[16:17], v[130:131], v[16:17]
	v_pk_fma_f32 v[60:61], v[58:59], v[78:79], v[60:61]
	v_pk_fma_f32 v[58:59], v[58:59], v[82:83], v[70:71]
	v_pk_fma_f32 v[20:21], v[80:81], v[44:45], v[20:21]
	v_pk_mul_f32 v[8:9], v[30:31], v[8:9]
	v_pk_mul_f32 v[2:3], v[90:91], v[2:3]
	s_waitcnt lgkmcnt(0)
	v_mov_b32_dpp v28, v4 row_shr:1 row_mask:0xf bank_mask:0xf
	v_mov_b32_dpp v29, v5 row_shr:1 row_mask:0xf bank_mask:0xf
	v_pk_mul_f32 v[14:15], v[68:69], v[14:15]
	v_pk_fma_f32 v[30:31], v[16:17], v[56:57], v[62:63]
	v_pk_fma_f32 v[18:19], v[94:95], v[76:77], v[60:61]
	v_pk_mul_f32 v[60:61], v[68:69], v[66:67]
	v_pk_fma_f32 v[58:59], v[94:95], v[78:79], v[58:59]
	v_pk_fma_f32 v[66:67], v[94:95], v[82:83], v[70:71]
	v_pk_fma_f32 v[20:21], v[74:75], v[40:41], v[20:21]
	v_pk_mul_f32 v[6:7], v[92:93], v[6:7]
	v_mov_b32_dpp v26, v2 row_shr:1 row_mask:0xf bank_mask:0xf
	v_mov_b32_dpp v27, v3 row_shr:1 row_mask:0xf bank_mask:0xf
	v_mov_b32_dpp v36, v8 row_shr:1 row_mask:0xf bank_mask:0xf
	v_mov_b32_dpp v37, v9 row_shr:1 row_mask:0xf bank_mask:0xf
	v_pk_mul_f32 v[12:13], v[88:89], v[12:13]
	v_pk_fma_f32 v[40:41], v[14:15], v[54:55], v[64:65]
	v_pk_fma_f32 v[30:31], v[52:53], v[28:29], v[30:31]
	v_pk_fma_f32 v[58:59], v[60:61], v[76:77], v[58:59]
	v_pk_fma_f32 v[66:67], v[60:61], v[78:79], v[66:67]
	v_pk_fma_f32 v[60:61], v[60:61], v[82:83], v[70:71]
	v_mov_b32_dpp v34, v6 row_shr:1 row_mask:0xf bank_mask:0xf
	v_mov_b32_dpp v35, v7 row_shr:1 row_mask:0xf bank_mask:0xf
	v_pk_mul_f32 v[10:11], v[86:87], v[10:11]
	v_pk_fma_f32 v[40:41], v[50:51], v[26:27], v[40:41]
	v_pk_fma_f32 v[30:31], v[48:49], v[36:37], v[30:31]
	v_pk_fma_f32 v[36:37], v[12:13], v[56:57], v[62:63]
	v_pk_fma_f32 v[66:67], v[76:77], v[42:43], v[66:67]
	v_pk_fma_f32 v[42:43], v[78:79], v[42:43], v[60:61]
	v_pk_fma_f32 v[34:35], v[46:47], v[34:35], v[40:41]
	v_pk_fma_f32 v[40:41], v[10:11], v[54:55], v[64:65]
	v_pk_fma_f32 v[36:37], v[16:17], v[52:53], v[36:37]
	v_pk_fma_f32 v[4:5], v[4:5], v[56:57], v[62:63]
	v_pk_fma_f32 v[38:39], v[76:77], v[38:39], v[42:43]
	v_pk_fma_f32 v[40:41], v[14:15], v[50:51], v[40:41]
	v_pk_fma_f32 v[28:29], v[48:49], v[28:29], v[36:37]
	v_pk_fma_f32 v[36:37], v[8:9], v[56:57], v[62:63]
	v_pk_fma_f32 v[2:3], v[2:3], v[54:55], v[64:65]
	v_pk_fma_f32 v[4:5], v[8:9], v[52:53], v[4:5]
	v_exp_f32_e64 v8, -v20
	v_exp_f32_e64 v9, -v21
	v_pk_fma_f32 v[26:27], v[46:47], v[26:27], v[40:41]
	v_pk_fma_f32 v[40:41], v[6:7], v[54:55], v[64:65]
	v_pk_fma_f32 v[2:3], v[6:7], v[50:51], v[2:3]
	v_exp_f32_e64 v6, -v38
	v_exp_f32_e64 v7, -v39
	v_pk_add_f32 v[8:9], v[8:9], 1.0 op_sel_hi:[1,0]
	v_pk_fma_f32 v[40:41], v[10:11], v[50:51], v[40:41]
	v_rcp_f32_e32 v8, v8
	v_pk_add_f32 v[6:7], v[6:7], 1.0 op_sel_hi:[1,0]
	v_rcp_f32_e32 v9, v9
	v_rcp_f32_e32 v6, v6
	v_rcp_f32_e32 v7, v7
	v_pk_fma_f32 v[2:3], v[10:11], v[46:47], v[2:3]
	v_pk_mul_f32 v[10:11], v[20:21], v[30:31]
	v_pk_fma_f32 v[24:25], v[74:75], v[44:45], v[24:25]
	v_pk_fma_f32 v[36:37], v[12:13], v[52:53], v[36:37]
	v_pk_fma_f32 v[4:5], v[12:13], v[48:49], v[4:5]
	v_pk_mul_f32 v[12:13], v[38:39], v[34:35]
	v_pk_mul_f32 v[8:9], v[8:9], v[10:11]
	v_exp_f32_e64 v10, -v66
	v_exp_f32_e64 v11, -v67
	v_pk_mul_f32 v[6:7], v[6:7], v[12:13]
	v_exp_f32_e64 v12, -v24
	v_exp_f32_e64 v13, -v25
	v_cvt_pk_bf16_f32 v244, v6, v7
	v_cvt_pk_bf16_f32 v245, v8, v9
	v_pk_add_f32 v[8:9], v[10:11], 1.0 op_sel_hi:[1,0]
	global_store_dwordx4 v[98:99], v[242:245], off
	v_pk_add_f32 v[6:7], v[12:13], 1.0 op_sel_hi:[1,0]
	v_rcp_f32_e32 v8, v8
	v_rcp_f32_e32 v9, v9
	v_rcp_f32_e32 v6, v6
	v_rcp_f32_e32 v7, v7
	v_pk_mul_f32 v[12:13], v[66:67], v[26:27]
	v_pk_mul_f32 v[10:11], v[24:25], v[28:29]
	v_pk_mul_f32 v[8:9], v[8:9], v[12:13]
	v_exp_f32_e64 v12, -v32
	v_exp_f32_e64 v13, -v33
	v_pk_mul_f32 v[6:7], v[6:7], v[10:11]
	v_exp_f32_e64 v10, -v58
	v_exp_f32_e64 v11, -v59
	v_cvt_pk_bf16_f32 v248, v8, v9
	v_cvt_pk_bf16_f32 v249, v6, v7
	v_pk_add_f32 v[6:7], v[12:13], 1.0 op_sel_hi:[1,0]
	global_store_dwordx4 v[102:103], v[246:249], off
	v_pk_add_f32 v[8:9], v[10:11], 1.0 op_sel_hi:[1,0]
	v_rcp_f32_e32 v6, v6
	v_rcp_f32_e32 v7, v7
	v_rcp_f32_e32 v8, v8
	v_rcp_f32_e32 v9, v9
	v_pk_fma_f32 v[16:17], v[16:17], v[48:49], v[36:37]
	v_pk_fma_f32 v[14:15], v[14:15], v[46:47], v[40:41]
	v_pk_mul_f32 v[10:11], v[32:33], v[16:17]
	v_pk_mul_f32 v[12:13], v[58:59], v[14:15]
	v_pk_mul_f32 v[6:7], v[10:11], v[6:7]
	v_exp_f32_e64 v10, -v18
	v_exp_f32_e64 v11, -v19
	v_pk_mul_f32 v[8:9], v[12:13], v[8:9]
	v_exp_f32_e64 v12, -v22
	v_exp_f32_e64 v13, -v23
	v_cvt_pk_bf16_f32 v252, v8, v9
	v_cvt_pk_bf16_f32 v253, v6, v7
	global_store_dwordx4 v[106:107], v[250:253], off
	v_pk_add_f32 v[8:9], v[10:11], 1.0 op_sel_hi:[1,0]
	v_pk_add_f32 v[6:7], v[12:13], 1.0 op_sel_hi:[1,0]
	v_rcp_f32_e32 v8, v8
	v_rcp_f32_e32 v9, v9
	v_rcp_f32_e32 v6, v6
	v_rcp_f32_e32 v7, v7
	v_pk_mul_f32 v[2:3], v[18:19], v[2:3]
	v_pk_mul_f32 v[4:5], v[22:23], v[4:5]
	v_pk_mul_f32 v[2:3], v[2:3], v[8:9]
	v_pk_mul_f32 v[4:5], v[4:5], v[6:7]
	v_cvt_pk_bf16_f32 v208, v2, v3
	s_andn2_b64 vcc, exec, s[2:3]
	v_cvt_pk_bf16_f32 v209, v4, v5
	global_store_dwordx4 v[108:109], v[206:209], off
	s_mov_b64 s[2:3], -1
	s_cbranch_vccnz .LBB0_1363
	s_and_b32 s2, s8, 1
	v_lshl_add_u32 v2, s30, 7, v1
	s_mul_i32 s3, s2, 0x1400
	v_ashrrev_i32_e32 v3, 31, v2
	s_add_i32 s3, s27, s3
	v_lshlrev_b64 v[2:3], 2, v[2:3]
	v_lshl_add_u64 v[4:5], v[138:139], 0, v[2:3]
	s_mov_b32 m0, s3
	v_lshl_add_u64 v[2:3], v[140:141], 0, v[2:3]
	global_load_lds_dword v[4:5], off
	s_add_i32 m0, s3, 0x800
	s_andn2_b64 vcc, exec, s[10:11]
	global_load_lds_dword v[2:3], off
	s_cbranch_vccnz .LBB0_1422
	s_lshl_b32 s6, s30, 8
	s_ashr_i32 s7, s6, 31
	v_lshl_add_u64 v[2:3], s[6:7], 2, v[150:151]
	s_add_i32 m0, s3, 0x1000
	s_nop 0
	global_load_lds_dword v[2:3], off

.LBB0_2100:
	s_or_b64 exec, exec, s[18:19]
	v_cvt_f32_i32_e32 v57, v57
	v_cvt_f32_i32_e32 v56, v56
	v_cvt_f32_i32_e32 v55, v55
	v_cvt_f32_i32_e32 v54, v54
	v_cvt_f32_i32_e32 v53, v53
	v_cvt_f32_i32_e32 v52, v52
	v_cvt_f32_i32_e32 v51, v51
	v_cvt_f32_i32_e32 v50, v50
	v_pk_mul_f32 v[56:57], v[130:131], v[56:57] op_sel_hi:[0,1]
	v_pk_fma_f32 v[190:191], v[56:57], v[200:201], v[202:203]
	v_pk_mul_f32 v[54:55], v[130:131], v[54:55] op_sel_hi:[0,1]
	v_pk_mul_f32 v[52:53], v[130:131], v[52:53] op_sel:[1,0]
	v_pk_fma_f32 v[190:191], v[114:115], v[68:69], v[190:191]
	v_pk_fma_f32 v[192:193], v[54:55], v[116:117], v[204:205]
	v_pk_fma_f32 v[72:73], v[110:111], v[72:73], v[190:191]
	v_pk_fma_f32 v[190:191], v[52:53], v[200:201], v[202:203]
	v_cvt_f32_i32_e32 v41, v41
	v_cvt_f32_i32_e32 v40, v40
	v_pk_mul_f32 v[50:51], v[130:131], v[50:51] op_sel:[1,0]
	v_pk_fma_f32 v[192:193], v[112:113], v[66:67], v[192:193]
	v_pk_fma_f32 v[190:191], v[56:57], v[114:115], v[190:191]
	v_pk_fma_f32 v[134:135], v[134:135], v[200:201], v[202:203]
	v_cvt_f32_i32_e32 v49, v49
	v_cvt_f32_i32_e32 v48, v48
	v_cvt_f32_i32_e32 v47, v47
	v_cvt_f32_i32_e32 v46, v46
	v_cvt_f32_i32_e32 v35, v35
	v_cvt_f32_i32_e32 v37, v37
	v_cvt_f32_i32_e32 v36, v36
	v_cvt_f32_i32_e32 v34, v34
	v_pk_fma_f32 v[70:71], v[108:109], v[70:71], v[192:193]
	v_pk_fma_f32 v[192:193], v[50:51], v[116:117], v[204:205]
	v_pk_fma_f32 v[68:69], v[110:111], v[68:69], v[190:191]
	v_pk_fma_f32 v[190:191], v[86:87], v[200:201], v[202:203]
	v_pk_fma_f32 v[86:87], v[86:87], v[114:115], v[134:135]
	v_cvt_f32_i32_e32 v39, v39
	v_cvt_f32_i32_e32 v38, v38
	v_pk_fma_f32 v[192:193], v[54:55], v[112:113], v[192:193]
	v_pk_fma_f32 v[190:191], v[52:53], v[114:115], v[190:191]
	v_pk_fma_f32 v[52:53], v[52:53], v[110:111], v[86:87]
	v_cvt_f32_i32_e32 v45, v45
	v_cvt_f32_i32_e32 v44, v44
	v_cvt_f32_i32_e32 v43, v43
	v_cvt_f32_i32_e32 v42, v42
	v_mov_b32_e32 v86, v132
	v_mov_b32_e32 v87, v132
	v_mov_b32_e32 v90, v133
	v_mov_b32_e32 v91, v133
	v_pk_fma_f32 v[66:67], v[108:109], v[66:67], v[192:193]
	v_pk_fma_f32 v[192:193], v[88:89], v[116:117], v[204:205]
	v_pk_fma_f32 v[116:117], v[136:137], v[116:117], v[204:205]
	v_pk_mul_f32 v[40:41], v[86:87], v[40:41]
	v_mov_b32_e32 v86, v133
	v_mov_b32_e32 v87, v133
	v_mov_b32_e32 v92, v132
	v_mov_b32_e32 v93, v132
	v_pk_fma_f32 v[88:89], v[88:89], v[112:113], v[116:117]
	v_pk_mul_f32 v[36:37], v[86:87], v[36:37]
	v_pk_mul_f32 v[34:35], v[90:91], v[34:35]
	v_pk_mul_f32 v[46:47], v[130:131], v[46:47] op_sel_hi:[0,1]
	v_pk_mul_f32 v[48:49], v[130:131], v[48:49] op_sel_hi:[0,1]
	v_pk_fma_f32 v[192:193], v[50:51], v[112:113], v[192:193]
	v_pk_fma_f32 v[50:51], v[50:51], v[108:109], v[88:89]
	v_pk_mul_f32 v[38:39], v[92:93], v[38:39]
	s_waitcnt lgkmcnt(0)
	v_mov_b32_dpp v58, v34 row_shr:1 row_mask:0xf bank_mask:0xf
	v_mov_b32_dpp v59, v35 row_shr:1 row_mask:0xf bank_mask:0xf
	v_mov_b32_dpp v60, v36 row_shr:1 row_mask:0xf bank_mask:0xf
	v_mov_b32_dpp v61, v37 row_shr:1 row_mask:0xf bank_mask:0xf
	v_pk_fma_f32 v[86:87], v[48:49], v[98:99], v[102:103]
	v_pk_fma_f32 v[88:89], v[46:47], v[84:85], v[106:107]
	v_mov_b32_dpp v62, v38 row_shr:1 row_mask:0xf bank_mask:0xf
	v_mov_b32_dpp v63, v39 row_shr:1 row_mask:0xf bank_mask:0xf
	v_mov_b32_dpp v64, v40 row_shr:1 row_mask:0xf bank_mask:0xf
	v_mov_b32_dpp v65, v41 row_shr:1 row_mask:0xf bank_mask:0xf
	v_pk_mul_f32 v[42:43], v[130:131], v[42:43] op_sel:[1,0]
	v_pk_mul_f32 v[44:45], v[130:131], v[44:45] op_sel:[1,0]
	v_pk_fma_f32 v[86:87], v[82:83], v[60:61], v[86:87]
	v_pk_fma_f32 v[88:89], v[80:81], v[58:59], v[88:89]
	v_pk_fma_f32 v[64:65], v[78:79], v[64:65], v[86:87]
	v_pk_fma_f32 v[62:63], v[76:77], v[62:63], v[88:89]
	v_pk_fma_f32 v[86:87], v[44:45], v[98:99], v[102:103]
	v_pk_fma_f32 v[88:89], v[42:43], v[84:85], v[106:107]
	v_pk_fma_f32 v[86:87], v[48:49], v[82:83], v[86:87]
	v_pk_fma_f32 v[88:89], v[46:47], v[80:81], v[88:89]
	v_pk_fma_f32 v[36:37], v[36:37], v[98:99], v[102:103]
	v_pk_fma_f32 v[34:35], v[34:35], v[84:85], v[106:107]
	v_pk_fma_f32 v[60:61], v[78:79], v[60:61], v[86:87]
	v_pk_fma_f32 v[58:59], v[76:77], v[58:59], v[88:89]
	v_pk_fma_f32 v[86:87], v[40:41], v[98:99], v[102:103]
	v_pk_fma_f32 v[88:89], v[38:39], v[84:85], v[106:107]
	v_pk_fma_f32 v[36:37], v[40:41], v[82:83], v[36:37]
	v_pk_fma_f32 v[34:35], v[38:39], v[80:81], v[34:35]
	v_exp_f32_e64 v38, -v70
	v_exp_f32_e64 v40, -v72
	v_exp_f32_e64 v41, -v73
	v_exp_f32_e64 v39, -v71
	v_pk_fma_f32 v[88:89], v[42:43], v[80:81], v[88:89]
	v_pk_fma_f32 v[86:87], v[44:45], v[82:83], v[86:87]
	v_pk_add_f32 v[40:41], v[40:41], 1.0 op_sel_hi:[1,0]
	v_pk_add_f32 v[38:39], v[38:39], 1.0 op_sel_hi:[1,0]
	v_rcp_f32_e32 v40, v40
	v_rcp_f32_e32 v38, v38
	v_rcp_f32_e32 v41, v41
	v_rcp_f32_e32 v39, v39
	v_pk_fma_f32 v[36:37], v[44:45], v[78:79], v[36:37]
	v_pk_fma_f32 v[34:35], v[42:43], v[76:77], v[34:35]
	v_pk_mul_f32 v[42:43], v[72:73], v[64:65]
	v_pk_mul_f32 v[44:45], v[70:71], v[62:63]
	v_pk_mul_f32 v[40:41], v[40:41], v[42:43]
	v_pk_mul_f32 v[38:39], v[38:39], v[44:45]
	v_exp_f32_e64 v44, -v66
	v_exp_f32_e64 v62, -v68
	v_exp_f32_e64 v63, -v69
	v_exp_f32_e64 v45, -v67
	v_pk_fma_f32 v[46:47], v[46:47], v[76:77], v[88:89]
	v_add_u32_e32 v76, 0x80, v188
	v_cvt_pk_bf16_f32 v242, v38, v39
	v_cvt_pk_bf16_f32 v243, v40, v41
	v_mov_b64_e32 v[40:41], s[58:59]
	v_mad_i64_i32 v[42:43], s[18:19], v76, s84, v[40:41]
	v_lshl_add_u64 v[98:99], v[42:43], 0, v[74:75]
	v_pk_add_f32 v[38:39], v[62:63], 1.0 op_sel_hi:[1,0]
	v_pk_add_f32 v[42:43], v[44:45], 1.0 op_sel_hi:[1,0]
	v_rcp_f32_e32 v38, v38
	v_rcp_f32_e32 v42, v42
	v_rcp_f32_e32 v39, v39
	v_rcp_f32_e32 v43, v43
	v_pk_fma_f32 v[56:57], v[56:57], v[110:111], v[190:191]
	v_pk_fma_f32 v[54:55], v[54:55], v[108:109], v[192:193]
	v_pk_mul_f32 v[44:45], v[68:69], v[60:61]
	v_pk_mul_f32 v[58:59], v[66:67], v[58:59]
	v_pk_mul_f32 v[38:39], v[38:39], v[44:45]
	v_pk_mul_f32 v[42:43], v[42:43], v[58:59]
	v_exp_f32_e64 v44, -v54
	v_exp_f32_e64 v58, -v56
	v_exp_f32_e64 v59, -v57
	v_exp_f32_e64 v45, -v55
	v_cvt_pk_bf16_f32 v246, v42, v43
	v_cvt_pk_bf16_f32 v247, v38, v39
	v_add_u32_e32 v38, 0x81, v188
	v_mad_i64_i32 v[38:39], s[18:19], v38, s84, v[40:41]
	v_lshl_add_u64 v[102:103], v[38:39], 0, v[74:75]
	v_pk_add_f32 v[38:39], v[58:59], 1.0 op_sel_hi:[1,0]
	v_pk_add_f32 v[42:43], v[44:45], 1.0 op_sel_hi:[1,0]
	v_rcp_f32_e32 v38, v38
	v_rcp_f32_e32 v42, v42
	v_rcp_f32_e32 v39, v39
	v_rcp_f32_e32 v43, v43
	v_pk_fma_f32 v[48:49], v[48:49], v[78:79], v[86:87]
	v_pk_mul_f32 v[44:45], v[54:55], v[46:47]
	v_pk_mul_f32 v[46:47], v[56:57], v[48:49]
	v_pk_mul_f32 v[42:43], v[44:45], v[42:43]
	v_pk_mul_f32 v[38:39], v[46:47], v[38:39]
	v_exp_f32_e64 v44, -v50
	v_exp_f32_e64 v46, -v52
	v_exp_f32_e64 v47, -v53
	v_exp_f32_e64 v45, -v51
	v_cvt_pk_bf16_f32 v250, v42, v43
	v_cvt_pk_bf16_f32 v251, v38, v39
	v_add_u32_e32 v38, 0x82, v188
	v_mad_i64_i32 v[38:39], s[18:19], v38, s84, v[40:41]
	v_lshl_add_u64 v[106:107], v[38:39], 0, v[74:75]
	v_pk_add_f32 v[38:39], v[46:47], 1.0 op_sel_hi:[1,0]
	v_pk_add_f32 v[42:43], v[44:45], 1.0 op_sel_hi:[1,0]
	v_rcp_f32_e32 v38, v38
	v_rcp_f32_e32 v42, v42
	v_rcp_f32_e32 v39, v39
	v_rcp_f32_e32 v43, v43
	v_pk_mul_f32 v[36:37], v[52:53], v[36:37]
	v_pk_mul_f32 v[34:35], v[50:51], v[34:35]
	v_pk_mul_f32 v[36:37], v[36:37], v[38:39]
	v_pk_mul_f32 v[34:35], v[34:35], v[42:43]
	v_mov_b32_e32 v66, 0
	v_cvt_pk_bf16_f32 v206, v34, v35
	v_cvt_pk_bf16_f32 v207, v36, v37
	v_add_u32_e32 v36, 0x83, v188
	v_mad_i64_i32 v[36:37], s[18:19], v36, s84, v[40:41]
	v_lshl_add_u64 v[108:109], v[36:37], 0, v[74:75]
	ds_read_b128 v[74:77], v241 offset:16
	ds_read_b128 v[50:53], v241 offset:528
	ds_read_b128 v[82:85], v241 offset:1040
	ds_read_b128 v[46:49], v241 offset:1552
	ds_read_b128 v[78:81], v241 offset:2064
	ds_read_b128 v[42:45], v241 offset:2576
	ds_read_b128 v[70:73], v241 offset:3088
	ds_read_b128 v[38:41], v241 offset:3600
	ds_read_b128 v[86:89], v241 offset:4112
	ds_read_b128 v[54:57], v241 offset:4624
	v_mov_b32_e32 v34, 0
	v_mov_b32_e32 v67, 0
	v_mov_b32_e32 v68, 0
	v_mov_b32_e32 v69, 0
	v_mov_b32_e32 v62, 0
	v_mov_b32_e32 v63, 0
	v_mov_b32_e32 v64, 0
	v_mov_b32_e32 v65, 0
	s_and_saveexec_b64 s[18:19], s[4:5]
	s_cbranch_execz .LBB0_2102
	ds_read_b128 v[66:69], v240 offset:128
	ds_read_b128 v[62:65], v240 offset:144

.LBB0_2108:
	s_or_b64 exec, exec, s[4:5]
	v_cvt_f32_i32_e32 v23, v23
	v_cvt_f32_i32_e32 v22, v22
	v_cvt_f32_i32_e32 v25, v25
	v_cvt_f32_i32_e32 v24, v24
	v_cvt_f32_i32_e32 v21, v21
	v_cvt_f32_i32_e32 v20, v20
	v_mov_b32_e32 v86, v131
	v_mov_b32_e32 v87, v131
	v_cvt_f32_i32_e32 v17, v17
	v_cvt_f32_i32_e32 v16, v16
	v_cvt_f32_i32_e32 v5, v5
	v_cvt_f32_i32_e32 v4, v4
	v_mov_b32_e32 v88, v131
	v_mov_b32_e32 v89, v131
	v_pk_mul_f32 v[94:95], v[86:87], v[22:23]
	v_pk_fma_f32 v[22:23], v[60:61], v[84:85], v[72:73]
	v_cvt_f32_i32_e32 v15, v15
	v_cvt_f32_i32_e32 v14, v14
	v_cvt_f32_i32_e32 v9, v9
	v_cvt_f32_i32_e32 v8, v8
	v_cvt_f32_i32_e32 v3, v3
	v_cvt_f32_i32_e32 v2, v2
	v_pk_mul_f32 v[24:25], v[88:89], v[24:25]
	v_pk_fma_f32 v[60:61], v[66:67], v[82:83], v[70:71]
	v_pk_fma_f32 v[22:23], v[32:33], v[80:81], v[22:23]
	v_cvt_f32_i32_e32 v67, v19
	v_cvt_f32_i32_e32 v66, v18
	v_mov_b32_e32 v131, v130
	v_pk_fma_f32 v[32:33], v[32:33], v[84:85], v[72:73]
	v_cvt_f32_i32_e32 v13, v13
	v_cvt_f32_i32_e32 v12, v12
	v_cvt_f32_i32_e32 v7, v7
	v_cvt_f32_i32_e32 v6, v6
	v_pk_fma_f32 v[22:23], v[24:25], v[74:75], v[22:23]
	v_pk_mul_f32 v[20:21], v[130:131], v[20:21]
	v_pk_fma_f32 v[32:33], v[24:25], v[80:81], v[32:33]
	v_pk_fma_f32 v[24:25], v[24:25], v[84:85], v[72:73]
	v_cvt_f32_i32_e32 v11, v11
	v_cvt_f32_i32_e32 v10, v10
	v_mov_b32_e32 v68, v130
	v_mov_b32_e32 v69, v130
	v_pk_fma_f32 v[32:33], v[20:21], v[74:75], v[32:33]
	v_pk_fma_f32 v[24:25], v[20:21], v[80:81], v[24:25]
	v_pk_fma_f32 v[20:21], v[20:21], v[84:85], v[72:73]
	v_pk_mul_f32 v[4:5], v[132:133], v[4:5]
	v_pk_mul_f32 v[16:17], v[130:131], v[16:17]
	v_pk_fma_f32 v[60:61], v[58:59], v[78:79], v[60:61]
	v_pk_fma_f32 v[58:59], v[58:59], v[82:83], v[70:71]
	v_pk_fma_f32 v[20:21], v[80:81], v[44:45], v[20:21]
	v_pk_mul_f32 v[8:9], v[30:31], v[8:9]
	v_pk_mul_f32 v[2:3], v[90:91], v[2:3]
	s_waitcnt lgkmcnt(0)
	v_mov_b32_dpp v28, v4 row_shr:1 row_mask:0xf bank_mask:0xf
	v_mov_b32_dpp v29, v5 row_shr:1 row_mask:0xf bank_mask:0xf
	v_pk_mul_f32 v[14:15], v[68:69], v[14:15]
	v_pk_fma_f32 v[30:31], v[16:17], v[56:57], v[62:63]
	v_pk_fma_f32 v[18:19], v[94:95], v[76:77], v[60:61]
	v_pk_mul_f32 v[60:61], v[68:69], v[66:67]
	v_pk_fma_f32 v[58:59], v[94:95], v[78:79], v[58:59]
	v_pk_fma_f32 v[66:67], v[94:95], v[82:83], v[70:71]
	v_pk_fma_f32 v[20:21], v[74:75], v[40:41], v[20:21]
	v_pk_mul_f32 v[6:7], v[92:93], v[6:7]
	v_mov_b32_dpp v26, v2 row_shr:1 row_mask:0xf bank_mask:0xf
	v_mov_b32_dpp v27, v3 row_shr:1 row_mask:0xf bank_mask:0xf
	v_mov_b32_dpp v36, v8 row_shr:1 row_mask:0xf bank_mask:0xf
	v_mov_b32_dpp v37, v9 row_shr:1 row_mask:0xf bank_mask:0xf
	v_pk_mul_f32 v[12:13], v[88:89], v[12:13]
	v_pk_fma_f32 v[40:41], v[14:15], v[54:55], v[64:65]
	v_pk_fma_f32 v[30:31], v[52:53], v[28:29], v[30:31]
	v_pk_fma_f32 v[58:59], v[60:61], v[76:77], v[58:59]
	v_pk_fma_f32 v[66:67], v[60:61], v[78:79], v[66:67]
	v_pk_fma_f32 v[60:61], v[60:61], v[82:83], v[70:71]
	v_mov_b32_dpp v34, v6 row_shr:1 row_mask:0xf bank_mask:0xf
	v_mov_b32_dpp v35, v7 row_shr:1 row_mask:0xf bank_mask:0xf
	v_pk_mul_f32 v[10:11], v[86:87], v[10:11]
	v_pk_fma_f32 v[40:41], v[50:51], v[26:27], v[40:41]
	v_pk_fma_f32 v[30:31], v[48:49], v[36:37], v[30:31]
	v_pk_fma_f32 v[36:37], v[12:13], v[56:57], v[62:63]
	v_pk_fma_f32 v[66:67], v[76:77], v[42:43], v[66:67]
	v_pk_fma_f32 v[42:43], v[78:79], v[42:43], v[60:61]
	v_pk_fma_f32 v[34:35], v[46:47], v[34:35], v[40:41]
	v_pk_fma_f32 v[40:41], v[10:11], v[54:55], v[64:65]
	v_pk_fma_f32 v[36:37], v[16:17], v[52:53], v[36:37]
	v_pk_fma_f32 v[4:5], v[4:5], v[56:57], v[62:63]
	v_pk_fma_f32 v[38:39], v[76:77], v[38:39], v[42:43]
	v_pk_fma_f32 v[40:41], v[14:15], v[50:51], v[40:41]
	v_pk_fma_f32 v[28:29], v[48:49], v[28:29], v[36:37]
	v_pk_fma_f32 v[36:37], v[8:9], v[56:57], v[62:63]
	v_pk_fma_f32 v[2:3], v[2:3], v[54:55], v[64:65]
	v_pk_fma_f32 v[4:5], v[8:9], v[52:53], v[4:5]
	v_exp_f32_e64 v8, -v20
	v_exp_f32_e64 v9, -v21
	v_pk_fma_f32 v[26:27], v[46:47], v[26:27], v[40:41]
	v_pk_fma_f32 v[40:41], v[6:7], v[54:55], v[64:65]
	v_pk_fma_f32 v[2:3], v[6:7], v[50:51], v[2:3]
	v_exp_f32_e64 v6, -v38
	v_exp_f32_e64 v7, -v39
	v_pk_add_f32 v[8:9], v[8:9], 1.0 op_sel_hi:[1,0]
	v_pk_fma_f32 v[40:41], v[10:11], v[50:51], v[40:41]
	v_rcp_f32_e32 v8, v8
	v_pk_add_f32 v[6:7], v[6:7], 1.0 op_sel_hi:[1,0]
	v_rcp_f32_e32 v9, v9
	v_rcp_f32_e32 v6, v6
	v_rcp_f32_e32 v7, v7
	v_pk_fma_f32 v[2:3], v[10:11], v[46:47], v[2:3]
	v_pk_mul_f32 v[10:11], v[20:21], v[30:31]
	v_pk_fma_f32 v[24:25], v[74:75], v[44:45], v[24:25]
	v_pk_fma_f32 v[36:37], v[12:13], v[52:53], v[36:37]
	v_pk_fma_f32 v[4:5], v[12:13], v[48:49], v[4:5]
	v_pk_mul_f32 v[12:13], v[38:39], v[34:35]
	v_pk_mul_f32 v[8:9], v[8:9], v[10:11]
	v_exp_f32_e64 v10, -v66
	v_exp_f32_e64 v11, -v67
	v_pk_mul_f32 v[6:7], v[6:7], v[12:13]
	v_exp_f32_e64 v12, -v24
	v_exp_f32_e64 v13, -v25
	v_cvt_pk_bf16_f32 v244, v6, v7
	v_cvt_pk_bf16_f32 v245, v8, v9
	v_pk_add_f32 v[8:9], v[10:11], 1.0 op_sel_hi:[1,0]
	global_store_dwordx4 v[98:99], v[242:245], off
	v_pk_add_f32 v[6:7], v[12:13], 1.0 op_sel_hi:[1,0]
	v_rcp_f32_e32 v8, v8
	v_rcp_f32_e32 v9, v9
	v_rcp_f32_e32 v6, v6
	v_rcp_f32_e32 v7, v7
	v_pk_mul_f32 v[12:13], v[66:67], v[26:27]
	v_pk_mul_f32 v[10:11], v[24:25], v[28:29]
	v_pk_mul_f32 v[8:9], v[8:9], v[12:13]
	v_exp_f32_e64 v12, -v32
	v_exp_f32_e64 v13, -v33
	v_pk_mul_f32 v[6:7], v[6:7], v[10:11]
	v_exp_f32_e64 v10, -v58
	v_exp_f32_e64 v11, -v59
	v_cvt_pk_bf16_f32 v248, v8, v9
	v_cvt_pk_bf16_f32 v249, v6, v7
	v_pk_add_f32 v[6:7], v[12:13], 1.0 op_sel_hi:[1,0]
	global_store_dwordx4 v[102:103], v[246:249], off
	v_pk_add_f32 v[8:9], v[10:11], 1.0 op_sel_hi:[1,0]
	v_rcp_f32_e32 v6, v6
	v_rcp_f32_e32 v7, v7
	v_rcp_f32_e32 v8, v8
	v_rcp_f32_e32 v9, v9
	v_pk_fma_f32 v[16:17], v[16:17], v[48:49], v[36:37]
	v_pk_fma_f32 v[14:15], v[14:15], v[46:47], v[40:41]
	v_pk_mul_f32 v[10:11], v[32:33], v[16:17]
	v_pk_mul_f32 v[12:13], v[58:59], v[14:15]
	v_pk_mul_f32 v[6:7], v[10:11], v[6:7]
	v_exp_f32_e64 v10, -v18
	v_exp_f32_e64 v11, -v19
	v_pk_mul_f32 v[8:9], v[12:13], v[8:9]
	v_exp_f32_e64 v12, -v22
	v_exp_f32_e64 v13, -v23
	v_cvt_pk_bf16_f32 v252, v8, v9
	v_cvt_pk_bf16_f32 v253, v6, v7
	global_store_dwordx4 v[106:107], v[250:253], off
	v_pk_add_f32 v[8:9], v[10:11], 1.0 op_sel_hi:[1,0]
	v_pk_add_f32 v[6:7], v[12:13], 1.0 op_sel_hi:[1,0]
	v_rcp_f32_e32 v8, v8
	v_rcp_f32_e32 v9, v9
	v_rcp_f32_e32 v6, v6
	v_rcp_f32_e32 v7, v7
	v_pk_mul_f32 v[2:3], v[18:19], v[2:3]
	v_pk_mul_f32 v[4:5], v[22:23], v[4:5]
	v_pk_mul_f32 v[2:3], v[2:3], v[8:9]
	v_pk_mul_f32 v[4:5], v[4:5], v[6:7]
	v_cvt_pk_bf16_f32 v208, v2, v3
	s_andn2_b64 vcc, exec, s[0:1]
	v_cvt_pk_bf16_f32 v209, v4, v5
	global_store_dwordx4 v[108:109], v[206:209], off
	s_mov_b64 s[0:1], -1
	s_cbranch_vccnz .LBB0_2052
	s_and_b32 s0, s85, 1
	v_lshl_add_u32 v2, s28, 7, v1
	s_mul_i32 s1, s0, 0x1400
	v_ashrrev_i32_e32 v3, 31, v2
	s_add_i32 s1, s25, s1
	v_lshlrev_b64 v[2:3], 2, v[2:3]
	v_lshl_add_u64 v[4:5], v[138:139], 0, v[2:3]
	s_mov_b32 m0, s1
	v_lshl_add_u64 v[2:3], v[140:141], 0, v[2:3]
	global_load_lds_dword v[4:5], off
	s_add_i32 m0, s1, 0x800
	s_andn2_b64 vcc, exec, s[8:9]
	global_load_lds_dword v[2:3], off
	s_cbranch_vccnz .LBB0_2111
	s_lshl_b32 s4, s28, 8
	s_ashr_i32 s5, s4, 31
	v_lshl_add_u64 v[2:3], s[4:5], 2, v[150:151]
	s_add_i32 m0, s1, 0x1000
	s_nop 0
	global_load_lds_dword v[2:3], off
